# GLA gate low-rank projection c_r.w2 moved from 128 VALU fmac + 48 broadcast loads per lane to 8 v_mfma_f32_16x16x4_f32 (f32 operands) + permlane16_swap
# speedup vs baseline: 1.0092x; 1.0041x over previous
.LBB0_190:
	s_cmpk_gt_i32 s20, 0xff
	s_mov_b64 s[2:3], -1
	s_cbranch_scc0 .LBB0_292
	s_lshl_b32 s6, s20, 1
	s_cmpk_gt_u32 s20, 0x2ff
	s_cbranch_scc0 .LBB0_231
	v_mov_b32_e32 v0, v206
	s_add_i32 s2, s6, 0xfffffa00
	v_ashrrev_i32_e32 v0, 8, v0
	v_mov_b32_e32 v106, v206
	v_mov_b32_e32 v111, v206
	v_add_u32_e32 v102, s2, v0
	v_mov_b32_e32 v1, v206
	v_bfe_u32 v2, v111, 6, 2
	s_movk_i32 s2, 0x100
	v_ashrrev_i32_e32 v0, 9, v102
	v_xor_b32_e32 v3, 3, v2
	v_cmp_gt_u32_e32 vcc, s2, v1
	v_ashrrev_i32_e32 v1, 31, v0
	v_and_b32_e32 v107, 15, v111
	v_cndmask_b32_e32 v108, v3, v2, vcc
	v_lshlrev_b64 v[100:101], 13, v[0:1]
	v_lshlrev_b32_e32 v0, 6, v102
	s_movk_i32 s2, 0x1fc0
	v_lshlrev_b32_e32 v113, 4, v108
	v_and_or_b32 v12, v0, s2, v100
	v_or_b32_e32 v110, v113, v107
	v_or_b32_e32 v100, v12, v110
	v_mov_b64_e32 v[0:1], s[68:69]
	v_bfe_u32 v8, v102, 7, 2
	v_mad_u64_u32 v[0:1], s[2:3], v100, s13, v[0:1]
	v_bfe_u32 v112, v111, 4, 2
	v_mad_i32_i24 v1, v101, s13, v1
	v_lshlrev_b32_e32 v176, 6, v8
	v_lshl_add_u64 v[0:1], v[0:1], 0, v[176:177]
	v_lshlrev_b32_e32 v2, 4, v112
	v_mov_b32_e32 v3, v177
	v_lshl_add_u64 v[0:1], v[0:1], 0, v[2:3]
	s_mov_b32 s2, 0x3e80000
	v_add_co_u32_e32 v0, vcc, s2, v0
	v_mov_b32_e32 v115, v206
	s_nop 0
	v_addc_co_u32_e32 v1, vcc, 0, v1, vcc
	global_load_dwordx4 v[0:3], v[0:1], off offset:3584
	v_lshlrev_b32_e32 v104, 7, v8
	v_bfe_u32 v116, v115, 2, 6
	v_lshlrev_b32_e32 v4, 4, v115
	v_and_b32_e32 v117, 48, v4
	v_or_b32_e32 v6, v12, v116
	v_mov_b64_e32 v[4:5], s[76:77]
	v_bfe_u32 v103, v115, 5, 3
	v_mad_u64_u32 v[6:7], s[2:3], v6, s13, v[4:5]
	v_mad_i32_i24 v7, v101, s13, v7
	v_mov_b32_e32 v105, v177
	v_lshlrev_b32_e32 v114, 3, v103
	v_lshlrev_b32_e32 v109, 5, v8
	v_lshl_add_u64 v[6:7], v[6:7], 0, v[104:105]
	v_lshlrev_b32_e32 v8, 1, v117
	v_mov_b32_e32 v9, v177
	v_or_b32_e32 v167, 1, v114
	v_lshl_add_u64 v[6:7], v[6:7], 0, v[8:9]
	s_mov_b64 s[2:3], 0x1000
	v_or_b32_e32 v8, v114, v12
	v_or_b32_e32 v12, v12, v167
	v_mov_b32_e32 v13, v101
	v_lshl_add_u64 v[158:159], v[6:7], 0, s[2:3]
	v_lshlrev_b64 v[14:15], 6, v[12:13]
	v_mad_u64_u32 v[12:13], s[2:3], v12, s13, v[4:5]
	v_and_b32_e32 v166, 31, v115
	v_mov_b32_e32 v9, v101
	v_readlane_b32 s4, v254, 15
	v_mad_i32_i24 v13, v101, s13, v13
	v_lshlrev_b64 v[10:11], 6, v[8:9]
	v_readlane_b32 s5, v254, 16
	v_lshlrev_b32_e32 v40, 1, v166
	v_mov_b32_e32 v41, v177
	v_lshl_add_u64 v[12:13], v[12:13], 0, v[176:177]
	v_lshl_add_u64 v[154:155], s[4:5], 0, v[10:11]
	v_lshl_add_u64 v[14:15], s[4:5], 0, v[14:15]
	v_lshl_add_u64 v[42:43], v[12:13], 0, v[40:41]
	v_or_b32_e32 v12, 2, v8
	v_mov_b32_e32 v13, v101
	v_lshlrev_b64 v[14:15], 6, v[12:13]
	v_mad_u64_u32 v[12:13], s[2:3], v12, s13, v[4:5]
	v_mad_i32_i24 v13, v101, s13, v13
	v_lshl_add_u64 v[12:13], v[12:13], 0, v[176:177]
	v_lshl_add_u64 v[58:59], v[12:13], 0, v[40:41]
	v_or_b32_e32 v12, 3, v8
	v_mov_b32_e32 v13, v101
	v_lshl_add_u64 v[56:57], s[4:5], 0, v[14:15]
	v_lshlrev_b64 v[14:15], 6, v[12:13]
	v_mad_u64_u32 v[12:13], s[2:3], v12, s13, v[4:5]
	v_mad_i32_i24 v13, v101, s13, v13
	v_lshl_add_u64 v[12:13], v[12:13], 0, v[176:177]
	v_lshl_add_u64 v[14:15], s[4:5], 0, v[14:15]
	v_lshl_add_u64 v[84:85], v[12:13], 0, v[40:41]
	v_or_b32_e32 v12, 4, v8
	v_mov_b32_e32 v13, v101
	v_lshlrev_b64 v[14:15], 6, v[12:13]
	v_mad_u64_u32 v[12:13], s[2:3], v12, s13, v[4:5]
	v_mad_i32_i24 v13, v101, s13, v13
	v_lshl_add_u64 v[12:13], v[12:13], 0, v[176:177]
	v_lshl_add_u64 v[156:157], v[12:13], 0, v[40:41]
	v_or_b32_e32 v12, 5, v8
	v_mov_b32_e32 v13, v101
	v_lshl_add_u64 v[86:87], s[4:5], 0, v[14:15]
	v_lshlrev_b64 v[14:15], 6, v[12:13]
	v_mad_u64_u32 v[12:13], s[2:3], v12, s13, v[4:5]
	v_mad_i32_i24 v13, v101, s13, v13
	v_lshl_add_u64 v[12:13], v[12:13], 0, v[176:177]
	v_lshl_add_u64 v[14:15], s[4:5], 0, v[14:15]
	v_lshl_add_u64 v[160:161], v[12:13], 0, v[40:41]
	v_or_b32_e32 v12, 6, v8
	v_mov_b32_e32 v13, v101
	v_mad_u64_u32 v[10:11], s[2:3], v8, s13, v[4:5]
	v_lshlrev_b64 v[14:15], 6, v[12:13]
	v_mad_u64_u32 v[12:13], s[2:3], v12, s13, v[4:5]
	v_or_b32_e32 v8, 7, v8
	v_mad_i32_i24 v13, v101, s13, v13
	v_mad_u64_u32 v[4:5], s[2:3], v8, s13, v[4:5]
	v_mad_i32_i24 v11, v101, s13, v11
	v_lshl_add_u64 v[12:13], v[12:13], 0, v[176:177]
	v_mad_i32_i24 v5, v101, s13, v5
	s_movk_i32 s2, 0x1000
	v_lshl_add_u64 v[10:11], v[10:11], 0, v[176:177]
	v_lshl_add_u64 v[164:165], v[12:13], 0, v[40:41]
	v_lshlrev_b64 v[12:13], 6, v[8:9]
	v_lshl_add_u64 v[4:5], v[4:5], 0, v[176:177]
	v_add_co_u32_e32 v6, vcc, s2, v6
	v_lshl_add_u64 v[10:11], v[10:11], 0, v[40:41]
	v_lshl_add_u64 v[162:163], s[4:5], 0, v[14:15]
	v_lshl_add_u64 v[24:25], s[4:5], 0, v[12:13]
	v_lshl_add_u64 v[4:5], v[4:5], 0, v[40:41]
	v_addc_co_u32_e32 v7, vcc, 0, v7, vcc
	s_nop 0
	s_nop 0
	global_load_ushort v168, v[10:11], off offset:3840
	global_load_ushort v169, v[42:43], off offset:3840
	global_load_ushort v170, v[58:59], off offset:3840
	global_load_ushort v171, v[84:85], off offset:3840
	s_nop 0
	s_nop 0
	global_load_ushort v172, v[156:157], off offset:3840
	global_load_ushort v173, v[160:161], off offset:3840
	s_nop 0
	global_load_ushort v162, v[164:165], off offset:3840
	global_load_ushort v163, v[4:5], off offset:3840
	global_load_dwordx4 v[8:11], v[6:7], off
	s_nop 0
	s_nop 0
	global_load_dwordx4 v[4:7], v[158:159], off offset:16
	v_lshl_add_u64 v[158:159], s[82:83], 0, v[104:105]
	v_lshlrev_b32_e32 v104, 2, v166
	v_or3_b32 v160, v109, s8, v166
	v_lshl_add_u64 v[158:159], v[158:159], 0, v[104:105]
	v_ashrrev_i32_e32 v161, 31, v160
	v_add_co_u32_e32 v158, vcc, s2, v158
	v_lshl_add_u64 v[160:161], v[160:161], 2, s[50:51]
	s_nop 0
	v_addc_co_u32_e32 v159, vcc, 0, v159, vcc
	global_load_dword v160, v[160:161], off
	s_nop 0
	s_nop 0
	v_readlane_b32 s4, v254, 15
	v_readlane_b32 s5, v254, 16
	v_lshlrev_b32_e32 v150, 6, v102
	v_and_b32_e32 v150, 0x1fc0, v150
	v_lshrrev_b32_e32 v151, 9, v102
	v_lshl_or_b32 v150, v151, 13, v150
	v_bfe_u32 v151, v206, 6, 2
	v_lshl_add_u32 v150, v151, 4, v150
	v_and_b32_e32 v151, 15, v206
	v_or_b32_e32 v150, v150, v151
	v_bfe_u32 v151, v206, 4, 2
	v_lshlrev_b32_e32 v150, 6, v150
	v_lshl_add_u32 v150, v151, 4, v150
	v_bfe_u32 v152, v102, 7, 2
	v_lshlrev_b32_e32 v152, 7, v152
	v_lshl_add_u32 v152, v151, 11, v152
	v_and_b32_e32 v153, 15, v206
	v_lshl_add_u32 v152, v153, 2, v152
	global_load_dwordx4 v[154:157], v150, s[4:5]
	global_load_dword v164, v152, s[82:83]
	global_load_dword v165, v152, s[82:83] offset:64
	global_load_dword v174, v152, s[82:83] offset:512
	global_load_dword v175, v152, s[82:83] offset:576
	global_load_dword v186, v152, s[82:83] offset:1024
	global_load_dword v187, v152, s[82:83] offset:1088
	global_load_dword v188, v152, s[82:83] offset:1536
	global_load_dword v189, v152, s[82:83] offset:1600
	s_waitcnt vmcnt(0)
	s_barrier
	s_mov_b32 s3, 0xbfb8aa3b
	s_mov_b32 s2, 0x3d800000
	v_cmp_gt_u32_sdwa s[4:5], v115, v219 src0_sel:BYTE_0 src1_sel:DWORD
	v_mfma_f32_16x16x4_f32 v[128:131], v154, v164, 0
	v_mfma_f32_16x16x4_f32 v[128:131], v155, v174, v[128:131]
	v_mfma_f32_16x16x4_f32 v[128:131], v156, v186, v[128:131]
	v_mfma_f32_16x16x4_f32 v[128:131], v157, v188, v[128:131]
	v_mfma_f32_16x16x4_f32 v[132:135], v154, v165, 0
	v_mfma_f32_16x16x4_f32 v[132:135], v155, v175, v[132:135]
	v_mfma_f32_16x16x4_f32 v[132:135], v156, v187, v[132:135]
	v_mfma_f32_16x16x4_f32 v[132:135], v157, v189, v[132:135]
	s_nop 15
	s_nop 15
	s_nop 7
	v_permlane16_swap_b32 v128, v132
	v_permlane16_swap_b32 v129, v133
	v_permlane16_swap_b32 v130, v134
	v_permlane16_swap_b32 v131, v135
	v_add_f32_e32 v118, v128, v160
	v_mul_f32_e64 v105, |v118|, s3
	v_exp_f32_e32 v105, v105
	v_add_f32_e32 v68, v131, v160
	v_add_f32_e32 v105, 1.0, v105
	v_mul_f32_e64 v69, |v68|, s3
	v_log_f32_e32 v120, v105
	v_exp_f32_e32 v69, v69
	v_add_f32_e32 v36, v133, v160
	v_mul_f32_e64 v37, |v36|, s3
	v_exp_f32_e32 v37, v37
	v_min_f32_e32 v118, 0, v118
	v_fmac_f32_e32 v118, 0xbf317218, v120
	v_mul_u32_u24_e32 v123, 0x108, v103
	v_add_f32_e32 v69, 1.0, v69
	v_lshrrev_b32_e32 v119, 8, v106
	v_fma_f32 v118, v118, s2, 0
	v_add_lshl_u32 v123, v123, v166, 2
	s_mov_b32 s2, 0xd800
	v_log_f32_e32 v69, v69
	v_lshlrev_b32_e32 v120, 16, v168
	v_add_f32_e32 v121, v129, v160
	v_mad_i32_i24 v123, v119, s2, v123
	v_add_f32_e32 v37, 1.0, v37
	v_mul_f32_e64 v122, |v121|, s3
	ds_write2st64_b32 v123, v118, v120 offset1:68
	v_min_f32_e32 v120, 0, v121
	v_log_f32_e32 v37, v37
	v_min_f32_e32 v68, 0, v68
	v_fmac_f32_e32 v68, 0xbf317218, v69
	v_min_f32_e32 v36, 0, v36
	v_fmac_f32_e32 v36, 0xbf317218, v37
	v_add_f32_e32 v88, v130, v160
	v_exp_f32_e32 v122, v122
	v_mul_f32_e64 v89, |v88|, s3
	v_exp_f32_e32 v89, v89
	v_add_f32_e32 v60, v132, v160
	v_mul_f32_e64 v61, |v60|, s3
	v_exp_f32_e32 v61, v61
	v_add_f32_e32 v28, v134, v160
	v_add_f32_e32 v122, 1.0, v122
	v_mul_f32_e64 v29, |v28|, s3
	v_add_f32_e32 v12, v135, v160
	v_log_f32_e32 v122, v122
	v_add_f32_e32 v89, 1.0, v89
	v_exp_f32_e32 v29, v29
	v_mul_f32_e64 v13, |v12|, s3
	v_log_f32_e32 v89, v89
	v_exp_f32_e32 v13, v13
	v_add_f32_e32 v61, 1.0, v61
	v_log_f32_e32 v61, v61
	v_fmac_f32_e32 v120, 0xbf317218, v122
	v_mul_u32_u24_e32 v91, 33, v167
	v_min_f32_e32 v88, 0, v88
	v_add_f32_e32 v29, 1.0, v29
	v_fmac_f32_e32 v118, 0x3d800000, v120
	v_add_lshl_u32 v91, v91, v166, 2
	v_fmac_f32_e32 v88, 0xbf317218, v89
	v_log_f32_e32 v29, v29
	v_add_f32_e32 v13, 1.0, v13
	v_mad_i32_i24 v91, v119, s2, v91
	v_fmamk_f32 v71, v88, 0x3d800000, v118
	v_min_f32_e32 v60, 0, v60
	v_log_f32_e32 v13, v13
	ds_write2_b32 v91, v118, v71 offset1:33
	v_fmac_f32_e32 v71, 0x3d800000, v68
	v_fmac_f32_e32 v60, 0xbf317218, v61
	v_lshlrev_b32_e32 v90, 16, v169
	v_lshlrev_b32_e32 v70, 16, v170
	v_add_u32_e32 v72, 0x4400, v91
	v_fmamk_f32 v39, v60, 0x3d800000, v71
	v_min_f32_e32 v28, 0, v28
	ds_write2_b32 v72, v90, v70 offset1:33
	v_lshlrev_b32_e32 v62, 16, v171
	v_lshlrev_b32_e32 v38, 16, v172
	ds_write2_b32 v91, v71, v39 offset0:66 offset1:99
	ds_write2_b32 v72, v62, v38 offset0:66 offset1:99
	v_fmac_f32_e32 v39, 0x3d800000, v36
	v_fmac_f32_e32 v28, 0xbf317218, v29
	v_min_f32_e32 v12, 0, v12
	v_fmamk_f32 v15, v28, 0x3d800000, v39
	v_fmac_f32_e32 v12, 0xbf317218, v13
	v_mul_i32_i24_e32 v105, 0xd800, v119
	v_lshlrev_b32_e32 v30, 16, v173
	v_lshlrev_b32_e32 v14, 16, v162
	ds_write2_b32 v91, v39, v15 offset0:132 offset1:165
	ds_write2_b32 v72, v30, v14 offset0:132 offset1:165
	v_fmac_f32_e32 v15, 0x3d800000, v12
	v_lshlrev_b32_e32 v12, 8, v103
	v_or3_b32 v12, v105, v12, v104
	v_lshlrev_b32_e32 v13, 16, v163
	ds_write_b32 v91, v15 offset:792
	ds_write_b32 v91, v13 offset:18200
	ds_write_b32 v12, v15 offset:53248
	v_mul_u32_u24_e32 v12, 0x48, v117
	v_lshlrev_b32_e32 v12, 1, v12
	v_mad_i32_i24 v12, v119, s2, v12
	v_mov_b32_e32 v106, 0
	v_lshl_or_b32 v12, v116, 1, v12
	ds_write_b16 v12, v8 offset:34816
	ds_write_b16_d16_hi v12, v8 offset:34960
	ds_write_b16 v12, v9 offset:35104
	ds_write_b16_d16_hi v12, v9 offset:35248
	ds_write_b16 v12, v10 offset:35392
	ds_write_b16_d16_hi v12, v10 offset:35536
	ds_write_b16 v12, v11 offset:35680
	ds_write_b16_d16_hi v12, v11 offset:35824
	ds_write_b16 v12, v4 offset:35968
	ds_write_b16_d16_hi v12, v4 offset:36112
	ds_write_b16 v12, v5 offset:36256
	ds_write_b16_d16_hi v12, v5 offset:36400
	ds_write_b16 v12, v6 offset:36544
	ds_write_b16_d16_hi v12, v6 offset:36688
	ds_write_b16 v12, v7 offset:36832
	ds_write_b16_d16_hi v12, v7 offset:36976
	s_waitcnt lgkmcnt(0)
	s_barrier
	s_and_saveexec_b64 s[2:3], s[4:5]
	s_cbranch_execz .LBB0_196
	s_mov_b32 s4, 0xd000
	v_add3_u32 v4, v105, v104, s4
	v_mov_b32_e32 v106, 0
	ds_read_b32 v220, v4
	ds_read_b32 v221, v4 offset:256
	ds_read_b32 v222, v4 offset:512
	ds_read_b32 v223, v4 offset:768
	ds_read_b32 v224, v4 offset:1024
	ds_read_b32 v225, v4 offset:1280
	ds_read_b32 v226, v4 offset:1536
	s_waitcnt lgkmcnt(0)
	v_add_f32_e32 v106, v106, v220
	v_cmp_lt_u32_e32 vcc, 1, v103
	s_nop 1
	v_cndmask_b32_e32 v221, 0, v221, vcc
	v_add_f32_e32 v106, v106, v221
	v_cmp_lt_u32_e32 vcc, 2, v103
	s_nop 1
	v_cndmask_b32_e32 v222, 0, v222, vcc
	v_add_f32_e32 v106, v106, v222
	v_cmp_lt_u32_e32 vcc, 3, v103
	s_nop 1
	v_cndmask_b32_e32 v223, 0, v223, vcc
	v_add_f32_e32 v106, v106, v223
	v_cmp_lt_u32_e32 vcc, 4, v103
	s_nop 1
	v_cndmask_b32_e32 v224, 0, v224, vcc
	v_add_f32_e32 v106, v106, v224
	v_cmp_lt_u32_e32 vcc, 5, v103
	s_nop 1
	v_cndmask_b32_e32 v225, 0, v225, vcc
	v_add_f32_e32 v106, v106, v225
	v_cmp_lt_u32_e32 vcc, 6, v103
	s_nop 1
	v_cndmask_b32_e32 v226, 0, v226, vcc
	v_add_f32_e32 v106, v106, v226
	v_mov_b32_e32 v103, 0
